# attention O tile staged through a wave-private LDS area: 16-byte stores cover 8 rows x 128B (8 lines) instead of 32 rows x 32B
# baseline (speedup 1.0000x reference)
; DI unsigned pk2(float lo, float hi) { return pg8::cvt_pk_bf16(lo, hi); }
; DI void attn_unit(LAS unsigned char* lds, const bf16* P, bf16* OG, float* LSE, const float* relb, int u) {
;     ...
;     l += __shfl_xor(l, 32);
;     const float inv = 1.0f / l;
;     bf16* orow = OG + (size_t)g * ((size_t)TH * 512) + qtok * 512 + hs * 128;
; #pragma unroll
;     for (int dt = 0; dt < 4; ++dt)
; #pragma unroll
;         for (int rq = 0; rq < 4; ++rq) { v2u wv; wv.x = pk2(O[dt][4 * rq] * inv, O[dt][4 * rq + 1] * inv); wv.y = pk2(O[dt][4 * rq + 2] * inv, O[dt][4 * rq + 3] * inv);
;             *(v2u*)(orow + 32 * dt + 8 * rq + 4 * hh) = wv; }
.LBB0_434:
	ds_bpermute_b32 v0, v184, v205
	s_ashr_i32 s7, s6, 31
	s_lshl_b64 s[6:7], s[6:7], 25
	s_add_u32 s6, s88, s6
	s_addc_u32 s7, s89, s7
	s_waitcnt lgkmcnt(0)
	v_add_f32_e32 v67, v205, v0
	v_div_scale_f32 v0, s[8:9], v67, v67, 1.0
	v_rcp_f32_e32 v68, v0
	s_and_b32 s5, s5, 0x180
	v_fma_f32 v69, -v0, v68, 1.0
	v_fmac_f32_e32 v68, v69, v68
	v_div_scale_f32 v69, vcc, 1.0, v67, 1.0
	v_mul_f32_e32 v70, v69, v68
	v_fma_f32 v71, -v0, v70, v69
	v_fmac_f32_e32 v70, v71, v68
	v_fma_f32 v0, -v0, v70, v69
	v_div_fmas_f32 v0, v0, v68, v70
	v_lshlrev_b64 v[68:69], 10, v[178:179]
	v_lshl_add_u64 v[68:69], s[6:7], 0, v[68:69]
	v_readlane_b32 s6, v254, 6
	v_readlane_b32 s7, v254, 7
	s_lshl_b32 s6, s5, 1
	v_div_fixup_f32 v70, v0, v67, 1.0
	v_lshl_add_u64 v[68:69], v[68:69], 0, s[6:7]
	v_lshrrev_b32_e32 v98, 3, v194
	v_and_b32_e32 v99, 7, v194
	v_and_b32_e32 v100, 31, v194
	v_lshrrev_b32_e32 v101, 5, v194
	v_lshrrev_b32_e32 v102, 6, v188
	v_mul_u32_u24_e32 v102, 0x1200, v102
	v_add_u32_e32 v102, 0x13800, v102
	v_mul_u32_u24_e32 v103, 0x90, v100
	v_add_u32_e32 v103, v103, v102
	v_lshl_add_u32 v103, v101, 4, v103
	v_mul_u32_u24_e32 v104, 0x90, v98
	v_add_u32_e32 v104, v104, v102
	v_lshl_add_u32 v104, v99, 4, v104
	v_lshlrev_b32_e32 v118, 4, v99
	v_mov_b32_e32 v119, 0
	v_add_u32_e32 v105, 0, v98
	v_lshlrev_b32_e32 v105, 2, v105
	ds_bpermute_b32 v106, v105, v178
	v_add_u32_e32 v105, 8, v98
	v_lshlrev_b32_e32 v105, 2, v105
	ds_bpermute_b32 v107, v105, v178
	v_add_u32_e32 v105, 16, v98
	v_lshlrev_b32_e32 v105, 2, v105
	ds_bpermute_b32 v108, v105, v178
	v_add_u32_e32 v105, 24, v98
	v_lshlrev_b32_e32 v105, 2, v105
	ds_bpermute_b32 v109, v105, v178
	s_waitcnt lgkmcnt(0)
	v_sub_u32_e32 v110, v106, v178
	v_ashrrev_i32_e32 v111, 31, v110
	v_lshlrev_b64 v[110:111], 10, v[110:111]
	v_lshl_add_u64 v[110:111], v[68:69], 0, v[110:111]
	v_lshl_add_u64 v[110:111], v[110:111], 0, v[118:119]
	v_sub_u32_e32 v112, v107, v178
	v_ashrrev_i32_e32 v113, 31, v112
	v_lshlrev_b64 v[112:113], 10, v[112:113]
	v_lshl_add_u64 v[112:113], v[68:69], 0, v[112:113]
	v_lshl_add_u64 v[112:113], v[112:113], 0, v[118:119]
	v_sub_u32_e32 v114, v108, v178
	v_ashrrev_i32_e32 v115, 31, v114
	v_lshlrev_b64 v[114:115], 10, v[114:115]
	v_lshl_add_u64 v[114:115], v[68:69], 0, v[114:115]
	v_lshl_add_u64 v[114:115], v[114:115], 0, v[118:119]
	v_sub_u32_e32 v116, v109, v178
	v_ashrrev_i32_e32 v117, 31, v116
	v_lshlrev_b64 v[116:117], 10, v[116:117]
	v_lshl_add_u64 v[116:117], v[68:69], 0, v[116:117]
	v_lshl_add_u64 v[116:117], v[116:117], 0, v[118:119]
	v_mul_f32_e32 v0, v50, v70
	v_mul_f32_e32 v50, v51, v70
	v_cvt_pk_bf16_f32 v50, v0, v50
	v_mul_f32_e32 v0, v52, v70
	v_mul_f32_e32 v51, v53, v70
	v_cvt_pk_bf16_f32 v51, v0, v51
	v_mul_f32_e32 v0, v54, v70
	v_mul_f32_e32 v52, v55, v70
	v_cvt_pk_bf16_f32 v52, v0, v52
	v_mul_f32_e32 v0, v56, v70
	v_mul_f32_e32 v53, v57, v70
	v_cvt_pk_bf16_f32 v53, v0, v53
	s_nop 1
	v_permlane32_swap_b32_e32 v50, v52
	v_permlane32_swap_b32_e32 v51, v53
	ds_write_b128 v103, v[50:53]
	v_mul_f32_e32 v0, v58, v70
	v_mul_f32_e32 v58, v59, v70
	v_cvt_pk_bf16_f32 v58, v0, v58
	v_mul_f32_e32 v0, v60, v70
	v_mul_f32_e32 v59, v61, v70
	v_cvt_pk_bf16_f32 v59, v0, v59
	v_mul_f32_e32 v0, v62, v70
	v_mul_f32_e32 v60, v63, v70
	v_cvt_pk_bf16_f32 v60, v0, v60
	v_mul_f32_e32 v0, v64, v70
	v_mul_f32_e32 v61, v65, v70
	v_cvt_pk_bf16_f32 v61, v0, v61
	s_nop 1
	v_permlane32_swap_b32_e32 v58, v60
	v_permlane32_swap_b32_e32 v59, v61
	ds_write_b128 v103, v[58:61] offset:32
	v_mul_f32_e32 v0, v34, v70
	v_mul_f32_e32 v34, v35, v70
	v_cvt_pk_bf16_f32 v34, v0, v34
	v_mul_f32_e32 v0, v36, v70
	v_mul_f32_e32 v35, v37, v70
	v_cvt_pk_bf16_f32 v35, v0, v35
	v_mul_f32_e32 v0, v38, v70
	v_mul_f32_e32 v36, v39, v70
	v_cvt_pk_bf16_f32 v36, v0, v36
	v_mul_f32_e32 v0, v40, v70
	v_mul_f32_e32 v37, v41, v70
	v_cvt_pk_bf16_f32 v37, v0, v37
	s_nop 1
	v_permlane32_swap_b32_e32 v34, v36
	v_permlane32_swap_b32_e32 v35, v37
	ds_write_b128 v103, v[34:37] offset:64
	v_mul_f32_e32 v0, v42, v70
	v_mul_f32_e32 v42, v43, v70
	v_cvt_pk_bf16_f32 v42, v0, v42
	v_mul_f32_e32 v0, v44, v70
	v_mul_f32_e32 v43, v45, v70
	v_cvt_pk_bf16_f32 v43, v0, v43
	v_mul_f32_e32 v0, v46, v70
	v_mul_f32_e32 v44, v47, v70
	v_cvt_pk_bf16_f32 v44, v0, v44
	v_mul_f32_e32 v0, v48, v70
	v_mul_f32_e32 v45, v49, v70
	v_cvt_pk_bf16_f32 v45, v0, v45
	s_nop 1
	v_permlane32_swap_b32_e32 v42, v44
	v_permlane32_swap_b32_e32 v43, v45
	ds_write_b128 v103, v[42:45] offset:96
	ds_read_b128 v[50:53], v104
	ds_read_b128 v[54:57], v104 offset:1152
	ds_read_b128 v[58:61], v104 offset:2304
	ds_read_b128 v[62:65], v104 offset:3456
	s_waitcnt lgkmcnt(0)
; DI unsigned pk2(float lo, float hi) { return pg8::cvt_pk_bf16(lo, hi); }
; DI void attn_unit(LAS unsigned char* lds, const bf16* P, bf16* OG, float* LSE, const float* relb, int u) {
;     ...
;     l += __shfl_xor(l, 32);
;     const float inv = 1.0f / l;
;     bf16* orow = OG + (size_t)g * ((size_t)TH * 512) + qtok * 512 + hs * 128;
; #pragma unroll
;     for (int dt = 0; dt < 4; ++dt)
; #pragma unroll
;         for (int rq = 0; rq < 4; ++rq) { v2u wv; wv.x = pk2(O[dt][4 * rq] * inv, O[dt][4 * rq + 1] * inv); wv.y = pk2(O[dt][4 * rq + 2] * inv, O[dt][4 * rq + 3] * inv);
;             *(v2u*)(orow + 32 * dt + 8 * rq + 4 * hh) = wv; }
;     if (hh == 0) LSE[qtok * 12 + head] = m * 0.6931471805599453f + __logf(l);
	global_store_dwordx4 v[110:111], v[50:53], off
	global_store_dwordx4 v[112:113], v[54:57], off
	global_store_dwordx4 v[114:115], v[58:61], off
	global_store_dwordx4 v[116:117], v[62:65], off
	s_nop 1
	v_mul_f32_e32 v0, v18, v70
	v_mul_f32_e32 v18, v19, v70
	v_cvt_pk_bf16_f32 v18, v0, v18
	v_mul_f32_e32 v0, v20, v70
	v_mul_f32_e32 v19, v21, v70
	v_cvt_pk_bf16_f32 v19, v0, v19
	v_mul_f32_e32 v0, v22, v70
	v_mul_f32_e32 v20, v23, v70
	v_cvt_pk_bf16_f32 v20, v0, v20
	v_mul_f32_e32 v0, v24, v70
	v_mul_f32_e32 v21, v25, v70
	v_cvt_pk_bf16_f32 v21, v0, v21
	s_nop 1
	v_permlane32_swap_b32_e32 v18, v20
	v_permlane32_swap_b32_e32 v19, v21
	ds_write_b128 v103, v[18:21]
	v_mul_f32_e32 v0, v26, v70
	v_mul_f32_e32 v26, v27, v70
	v_cvt_pk_bf16_f32 v26, v0, v26
	v_mul_f32_e32 v0, v28, v70
	v_mul_f32_e32 v27, v29, v70
	v_cvt_pk_bf16_f32 v27, v0, v27
	v_mul_f32_e32 v0, v30, v70
	v_mul_f32_e32 v28, v31, v70
	v_cvt_pk_bf16_f32 v28, v0, v28
	v_mul_f32_e32 v0, v32, v70
	v_mul_f32_e32 v29, v33, v70
	v_cvt_pk_bf16_f32 v29, v0, v29
	s_nop 1
	v_permlane32_swap_b32_e32 v26, v28
	v_permlane32_swap_b32_e32 v27, v29
	ds_write_b128 v103, v[26:29] offset:32
	v_mul_f32_e32 v0, v2, v70
	v_mul_f32_e32 v2, v3, v70
	v_cvt_pk_bf16_f32 v2, v0, v2
	v_mul_f32_e32 v0, v4, v70
	v_mul_f32_e32 v3, v5, v70
	v_cvt_pk_bf16_f32 v3, v0, v3
	v_mul_f32_e32 v0, v6, v70
	v_mul_f32_e32 v4, v7, v70
	v_cvt_pk_bf16_f32 v4, v0, v4
	v_mul_f32_e32 v0, v8, v70
	v_mul_f32_e32 v5, v9, v70
	v_cvt_pk_bf16_f32 v5, v0, v5
	s_nop 1
	v_permlane32_swap_b32_e32 v2, v4
	v_permlane32_swap_b32_e32 v3, v5
	ds_write_b128 v103, v[2:5] offset:64
	v_mul_f32_e32 v0, v10, v70
	v_mul_f32_e32 v10, v11, v70
	v_cvt_pk_bf16_f32 v10, v0, v10
	v_mul_f32_e32 v0, v12, v70
	v_mul_f32_e32 v11, v13, v70
	v_cvt_pk_bf16_f32 v11, v0, v11
	v_mul_f32_e32 v0, v14, v70
	v_mul_f32_e32 v12, v15, v70
	v_cvt_pk_bf16_f32 v12, v0, v12
	v_mul_f32_e32 v0, v16, v70
	v_mul_f32_e32 v13, v17, v70
	v_cvt_pk_bf16_f32 v13, v0, v13
	s_nop 1
	v_permlane32_swap_b32_e32 v10, v12
	v_permlane32_swap_b32_e32 v11, v13
	ds_write_b128 v103, v[10:13] offset:96
	ds_read_b128 v[50:53], v104
	ds_read_b128 v[54:57], v104 offset:1152
	ds_read_b128 v[58:61], v104 offset:2304
	ds_read_b128 v[62:65], v104 offset:3456
	s_waitcnt lgkmcnt(0)
	global_store_dwordx4 v[110:111], v[50:53], off offset:128
	global_store_dwordx4 v[112:113], v[54:57], off offset:128
	global_store_dwordx4 v[114:115], v[58:61], off offset:128
	global_store_dwordx4 v[116:117], v[62:65], off offset:128
	s_nop 1
	s_mov_b32 s5, s7
	v_writelane_b32 v254, s4, 6
	s_nop 0
	v_writelane_b32 v254, s5, 7
	v_cmp_eq_u32_e32 vcc, 0, v183
	s_nop 1
	s_and_saveexec_b64 s[6:7], vcc
	s_cbranch_execz .LBB0_436
	s_mov_b32 s5, 0x800000
	v_cmp_gt_f32_e32 vcc, s5, v67
	s_mov_b32 s5, 0x3f317217
	s_nop 0
	v_cndmask_b32_e64 v0, 0, 32, vcc
	v_ldexp_f32 v0, v67, v0
	v_log_f32_e32 v0, v0
	v_cndmask_b32_e32 v2, 0, v195, vcc
	v_mul_f32_e32 v3, 0x3f317217, v0
	v_fma_f32 v3, v0, s5, -v3
	v_fmac_f32_e32 v3, 0x3377d1cf, v0
	s_mov_b32 s5, 0x7f800000
	v_fmac_f32_e32 v3, 0x3f317217, v0
	v_cmp_lt_f32_e64 vcc, |v0|, s5
	s_ashr_i32 s5, s4, 31
	s_nop 0
	v_cndmask_b32_e32 v0, v0, v3, vcc
	v_sub_f32_e32 v6, v0, v2
	v_mad_u64_u32 v[2:3], s[8:9], v178, 48, s[90:91]
	v_mov_b32_e32 v0, v3
	v_mad_u64_u32 v[4:5], s[8:9], v179, 48, v[0:1]
	v_mov_b32_e32 v3, v4
	v_fmac_f32_e32 v6, 0x3f317218, v66
	v_lshl_add_u64 v[2:3], s[4:5], 2, v[2:3]
	global_store_dword v[2:3], v6, off
